# plus: per-step out/ws pointers fetched with s_load (scalar cache) instead of flat load + readfirstlane
# speedup vs baseline: 1.0173x; 1.0052x over previous
; __global__ void __launch_bounds__(NTHR, 2) fwd_megakernel(Args args) {
;     ...
;         unsigned char* ws = uni(args_.ws);
;         float* out = uni(args_.out);
;         bool chip_wide = false;
;         if (step == 0) {
;             if (F.bx == 0) for (int i = F.tid; i < XCD_BAR_WORDS + 1024; i += NTHR) ((unsigned*)(ws + WS_BAR))[i] = 0u;
;             p0_prologue(F, args_, ws);
;         } else {
;             const int sidx = step - 1, l = sidx / STEPS_PER_LAYER, ps = sidx % STEPS_PER_LAYER;
;             int kind, hf = 0;
;             if (ps < 4) kind = ps; else if (ps < 18) { hf = (ps - 4) / 7; kind = 4 + (ps - 4) % 7; } else kind = 11 + (ps - 18);
.LBB0_9:
	s_load_dwordx2 s[30:31], s[0:1], 0xb8
	s_load_dwordx2 s[76:77], s[0:1], 0xc0
	s_ashr_i32 s83, s2, 6
	s_cmp_lg_u32 s75, 0
	s_cselect_b64 s[78:79], -1, 0
	v_and_b32_e32 v198, 63, v196
	s_and_b64 vcc, exec, s[78:79]
	s_waitcnt vmcnt(0) lgkmcnt(0)
	s_cbranch_vccz .LBB0_46
	v_sub_co_u32_e64 v0, s[4:5], s75, 22
	s_add_i32 s2, s75, -1
	s_nop 0
	v_writelane_b32 v248, s4, 14
	s_mov_b32 s16, 0
	s_nop 0
	v_writelane_b32 v248, s5, 15
	s_and_b64 s[4:5], s[4:5], exec
	v_readfirstlane_b32 s4, v0
	s_cselect_b32 s5, s2, s4
	s_cmp_lt_i32 s5, 4
	s_cbranch_scc1 .LBB0_16
	s_cmp_gt_u32 s5, 17
	s_mov_b64 s[6:7], -1
	s_cbranch_scc0 .LBB0_13
	s_add_i32 s4, s5, -7
	s_mov_b64 s[6:7], 0
